# h3 ctx direct conv: u-row loads issued before the wait on the filter-tap loads (wait vmcnt(8)); tap-register shuffles moved after the wait
# baseline (speedup 1.0000x reference)
; __device__ __forceinline__ void h3_longconv(const KQ p_in, int o, bool ctx_full, unsigned char* smem) {
;     ...
;             for (int mb = 0; mb < CL; mb += 8) {
;                 float kk[15], uu[8];
; #pragma unroll
;                 for (int q = 0; q < 15; ++q) { const int lag = n0 - mb - 7 + q;
;                     kk[q] = (lag >= 0) ? ((lag < CL) ? kf[(size_t)lag * D + d] : 0.f) : ((-lag < CL) ? kf[(size_t)(CL - lag) * D + d] : 0.f); }
; #pragma unroll
;                 for (int u = 0; u < 8; ++u) uu[u] = up[(size_t)(mb + u) * D];
; #pragma unroll
;                 for (int u = 0; u < 8; ++u)
; #pragma unroll
;                     for (int j = 0; j < 8; ++j) acc[j] += uu[u] * kk[7 - u + j];
.LBB0_526:
	s_or_b64 exec, exec, s[22:23]
	v_lshl_add_u64 v[52:53], v[16:17], 0, s[20:21]
	v_add_co_u32_e32 v46, vcc, 0x131b4000, v52
	s_nop 1
	v_addc_co_u32_e32 v47, vcc, 0, v53, vcc
	global_load_dword v54, v[46:47], off
	v_add_co_u32_e32 v46, vcc, 0x131b5000, v52
	s_nop 1
	v_addc_co_u32_e32 v47, vcc, 0, v53, vcc
	global_load_dword v56, v[46:47], off
	v_add_co_u32_e32 v46, vcc, 0x131b6000, v52
	s_nop 1
	v_addc_co_u32_e32 v47, vcc, 0, v53, vcc
	global_load_dword v48, v[46:47], off
	v_add_co_u32_e32 v46, vcc, 0x131b7000, v52
	s_nop 1
	v_addc_co_u32_e32 v47, vcc, 0, v53, vcc
	v_add_co_u32_e32 v50, vcc, 0x131b8000, v52
	s_nop 1
	global_load_dword v46, v[46:47], off
	v_addc_co_u32_e32 v51, vcc, 0, v53, vcc
	v_add_co_u32_e32 v58, vcc, 0x131b9000, v52
	s_nop 1
	global_load_dword v50, v[50:51], off
	v_addc_co_u32_e32 v59, vcc, 0, v53, vcc
	global_load_dword v40, v[58:59], off
	v_add_co_u32_e32 v58, vcc, 0x131ba000, v52
	s_nop 1
	v_addc_co_u32_e32 v59, vcc, 0, v53, vcc
	v_add_co_u32_e32 v52, vcc, 0x131bb000, v52
	s_nop 1
	global_load_dword v42, v[58:59], off
	v_addc_co_u32_e32 v53, vcc, 0, v53, vcc
	global_load_dword v44, v[52:53], off
	s_waitcnt vmcnt(8) lgkmcnt(0)
	v_mov_b32_e32 v28, v33
	v_mov_b32_e32 v30, v29
	v_mov_b32_e32 v26, v31
	v_mov_b32_e32 v24, v27
	v_mov_b32_e32 v22, v25
	v_mov_b32_e32 v20, v23
	v_mov_b32_e32 v18, v21
	s_add_i32 s2, s2, 8
	s_add_u32 s20, s20, 0x8000
	s_addc_u32 s21, s21, 0
	s_add_i32 s30, s30, 8
	v_add_u32_e32 v9, -8, v9
	s_cmpk_gt_u32 s30, 0xf7
	s_waitcnt lgkmcnt(0)
	s_waitcnt vmcnt(7)
	v_pk_fma_f32 v[14:15], v[32:33], v[54:55], v[14:15] op_sel_hi:[1,0,1]
	v_pk_fma_f32 v[6:7], v[34:35], v[54:55], v[6:7] op_sel_hi:[1,0,1]
	v_pk_fma_f32 v[4:5], v[36:37], v[54:55], v[4:5] op_sel_hi:[1,0,1]
	v_pk_fma_f32 v[2:3], v[38:39], v[54:55], v[2:3] op_sel_hi:[1,0,1]
	s_waitcnt vmcnt(6)
	v_pk_fma_f32 v[14:15], v[28:29], v[56:57], v[14:15] op_sel_hi:[1,0,1]
	s_nop 0
	s_waitcnt vmcnt(5)
	v_pk_fma_f32 v[14:15], v[30:31], v[48:49], v[14:15] op_sel_hi:[1,0,1]
	s_nop 0
	s_waitcnt vmcnt(4)
	v_pk_fma_f32 v[14:15], v[26:27], v[46:47], v[14:15] op_sel_hi:[1,0,1]
	s_nop 0
	s_waitcnt vmcnt(3)
	v_pk_fma_f32 v[14:15], v[24:25], v[50:51], v[14:15] op_sel_hi:[1,0,1]
	s_nop 0
	s_waitcnt vmcnt(2)
	v_pk_fma_f32 v[14:15], v[22:23], v[40:41], v[14:15] op_sel_hi:[1,0,1]
	s_nop 0
	s_waitcnt vmcnt(1)
	v_pk_fma_f32 v[14:15], v[20:21], v[42:43], v[14:15] op_sel_hi:[1,0,1]
	v_mov_b32_e32 v20, v37
	v_mov_b32_e32 v21, v34
	s_waitcnt vmcnt(0)
	v_pk_fma_f32 v[14:15], v[18:19], v[44:45], v[14:15] op_sel_hi:[1,0,1]
	v_mov_b32_e32 v18, v35
	v_mov_b32_e32 v19, v32
	v_pk_fma_f32 v[6:7], v[18:19], v[56:57], v[6:7] op_sel_hi:[1,0,1]
	v_pk_fma_f32 v[4:5], v[20:21], v[56:57], v[4:5] op_sel_hi:[1,0,1]
	v_pk_fma_f32 v[6:7], v[32:33], v[48:49], v[6:7] op_sel_hi:[1,0,1]
	v_pk_fma_f32 v[4:5], v[34:35], v[48:49], v[4:5] op_sel_hi:[1,0,1]
	v_pk_fma_f32 v[6:7], v[28:29], v[46:47], v[6:7] op_sel_hi:[1,0,1]
	v_pk_fma_f32 v[4:5], v[18:19], v[46:47], v[4:5] op_sel_hi:[1,0,1]
	v_pk_fma_f32 v[6:7], v[30:31], v[50:51], v[6:7] op_sel_hi:[1,0,1]
	v_pk_fma_f32 v[4:5], v[32:33], v[50:51], v[4:5] op_sel_hi:[1,0,1]
	v_pk_fma_f32 v[6:7], v[26:27], v[40:41], v[6:7] op_sel_hi:[1,0,1]
	v_pk_fma_f32 v[4:5], v[28:29], v[40:41], v[4:5] op_sel_hi:[1,0,1]
	v_pk_fma_f32 v[6:7], v[24:25], v[42:43], v[6:7] op_sel_hi:[1,0,1]
	v_pk_fma_f32 v[4:5], v[30:31], v[42:43], v[4:5] op_sel_hi:[1,0,1]
	v_pk_fma_f32 v[6:7], v[22:23], v[44:45], v[6:7] op_sel_hi:[1,0,1]
	v_mov_b32_e32 v22, v39
	v_mov_b32_e32 v23, v36
	v_pk_fma_f32 v[2:3], v[22:23], v[56:57], v[2:3] op_sel_hi:[1,0,1]
	v_pk_fma_f32 v[4:5], v[26:27], v[44:45], v[4:5] op_sel_hi:[1,0,1]
	v_pk_fma_f32 v[2:3], v[36:37], v[48:49], v[2:3] op_sel_hi:[1,0,1]
	s_nop 0
	v_pk_fma_f32 v[2:3], v[20:21], v[46:47], v[2:3] op_sel_hi:[1,0,1]
	s_nop 0
	v_pk_fma_f32 v[2:3], v[34:35], v[50:51], v[2:3] op_sel_hi:[1,0,1]
	s_nop 0
	v_pk_fma_f32 v[2:3], v[18:19], v[40:41], v[2:3] op_sel_hi:[1,0,1]
	s_nop 0
	v_pk_fma_f32 v[2:3], v[32:33], v[42:43], v[2:3] op_sel_hi:[1,0,1]
	v_add_u32_e32 v43, 0xffff8000, v43
	v_pk_fma_f32 v[2:3], v[28:29], v[44:45], v[2:3] op_sel_hi:[1,0,1]
	s_cbranch_scc1 .LBB0_524
